# rw_chunk_prep: loads of tokens 1..3 of each 4-token group issued together with token 0 (five fewer serialized round trips per group)
# speedup vs baseline: 1.0178x; 1.0077x over previous
; __device__ __forceinline__ f32x4 bf4(v2u u) { return (f32x4){bflo(u.x), bfhi(u.x), bflo(u.y), bfhi(u.y)}; }
; __device__ __forceinline__ void rw_chunk_prep(const Args& a, int head, int tc0, const LAS bf16* TDr, const LAS bf16* DAr, LAS unsigned char* lw_, int lane) {
;     ...
;         for (int i = 0; i < 4; ++i) {
;             const int tt = tt0 + i;
;             const f32x4 zr = bf4(*(const v2u*)(ZA + (size_t)tt * 3072 + cbase)), zk = bf4(*(const v2u*)(ZA + (size_t)tt * 3072 + 1024 + cbase)), zv = bf4(*(const v2u*)(ZA + (size_t)tt * 3072 + 2048 + cbase));
;             const f32x4 r = zr + (pr - zr) * mur, k = zk + (pk - zk) * muk, v = zv + (pv - zv) * muv;
;             pr = zr; pk = zk; pv = zv;
;             f32x4 lwv, alr;
; #pragma unroll
;             for (int cb = 0; cb < 4; ++cb) { const float x = -(w0[cb] + accw[cb][i]); const float sp = fmaxf(x, 0.f) + __logf(1.f + __expf(-fabsf(x))); lwv[cb] = -__expf(-sp - 0.5f); alr[cb] = __builtin_amdgcn_rcpf(1.f + __expf(-(a0[cb] + acca[cb][i]))); }
;             const f32x4 kkr = k * kkw, kmod = k * (1.f + (alr - 1.f) * kaw);
;             float ssq = (kkr.x * kkr.x + kkr.y * kkr.y) + (kkr.z * kkr.z + kkr.w * kkr.w);
;             const f32x4 rkk = r * kmod * rkw; float rkp = (rkk.x + rkk.y) + (rkk.z + rkk.w);
;             ssq = row16_sum(ssq); rkp = row16_sum(rkp);
;             const float inv = __builtin_amdgcn_rsqf(fmaxf(ssq, 1e-24f));
;             const f32x4 kk = kkr * inv;
;             rr[i] = r; km[i] = kmod; av[i] = -kk; bv[i] = kk * alr; lw[i] = lwv; vv[i] = v;
;             if (j == 0) RK[(size_t)tt * 16 + head] = rkp;
.LBB0_335:
	s_or_b64 exec, exec, s[2:3]
	v_mov_b64_e32 v[96:97], s[72:73]
	v_mad_i64_i32 v[96:97], s[2:3], v106, s44, v[96:97]
	v_lshl_add_u64 v[96:97], v[96:97], 0, v[66:67]
	global_load_dwordx2 v[108:109], v[96:97], off
	global_load_dwordx2 v[110:111], v[96:97], off offset:2048
	v_add_co_u32_e32 v96, vcc, s45, v96
	s_waitcnt vmcnt(8)
	v_add_f32_e32 v107, v24, v60
	v_addc_co_u32_e32 v97, vcc, 0, v97, vcc
	global_load_dwordx2 v[96:97], v[96:97], off
	v_mov_b32_e32 v230, s45
	v_mov_b32_e32 v231, 0
	v_or_b32_e32 v224, 1, v106
	v_mov_b64_e32 v[226:227], s[72:73]
	v_mad_i64_i32 v[226:227], s[2:3], v224, s44, v[226:227]
	v_lshl_add_u64 v[226:227], v[226:227], 0, v[66:67]
	v_lshl_add_u64 v[228:229], v[226:227], 0, v[230:231]
	global_load_dwordx2 v[206:207], v[226:227], off
	global_load_dwordx2 v[208:209], v[226:227], off offset:2048
	global_load_dwordx2 v[210:211], v[228:229], off
	v_or_b32_e32 v224, 2, v106
	v_mov_b64_e32 v[232:233], s[72:73]
	v_mad_i64_i32 v[232:233], s[2:3], v224, s44, v[232:233]
	v_lshl_add_u64 v[232:233], v[232:233], 0, v[66:67]
	v_lshl_add_u64 v[234:235], v[232:233], 0, v[230:231]
	global_load_dwordx2 v[212:213], v[232:233], off
	global_load_dwordx2 v[214:215], v[232:233], off offset:2048
	global_load_dwordx2 v[216:217], v[234:235], off
	v_or_b32_e32 v224, 3, v106
	v_mov_b64_e32 v[238:239], s[72:73]
	v_mad_i64_i32 v[238:239], s[2:3], v224, s44, v[238:239]
	v_lshl_add_u64 v[238:239], v[238:239], 0, v[66:67]
	v_lshl_add_u64 v[240:241], v[238:239], 0, v[230:231]
	global_load_dwordx2 v[218:219], v[238:239], off
	global_load_dwordx2 v[220:221], v[238:239], off offset:2048
	global_load_dwordx2 v[222:223], v[240:241], off
	v_add_f32_e32 v28, v28, v61
	v_add_f32_e32 v32, v32, v62
	v_add_f32_e32 v56, v56, v63
	v_mul_f32_e32 v107, 0xbfb8aa3b, v107
	v_mul_f32_e32 v28, 0xbfb8aa3b, v28
	v_mul_f32_e32 v32, 0xbfb8aa3b, v32
	v_mul_f32_e32 v56, 0xbfb8aa3b, v56
	v_exp_f32_e32 v107, v107
	v_exp_f32_e32 v28, v28
	v_exp_f32_e32 v32, v32
	v_exp_f32_e32 v56, v56
	v_add_f32_e32 v107, 1.0, v107
	v_add_f32_e32 v28, 1.0, v28
	v_add_f32_e32 v32, 1.0, v32
	v_add_f32_e32 v56, 1.0, v56
	v_rcp_f32_e32 v112, v107
	v_rcp_f32_e32 v114, v32
	v_rcp_f32_e32 v115, v56
	v_rcp_f32_e32 v113, v28
	s_lshl_b64 s[2:3], s[0:1], 2
	v_mov_b32_e32 v190, v67
	v_pk_add_f32 v[116:117], v[114:115], -1.0 op_sel_hi:[1,0]
	v_pk_add_f32 v[118:119], v[112:113], -1.0 op_sel_hi:[1,0]
	s_waitcnt vmcnt(16)
	v_pk_fma_f32 v[130:131], v[54:55], v[116:117], 1.0 op_sel_hi:[1,1,0]
	v_pk_fma_f32 v[128:129], v[52:53], v[118:119], 1.0 op_sel_hi:[1,1,0]
	v_mov_b32_e32 v24, v67
	s_add_u32 s26, s35, s2
	s_addc_u32 s27, s36, s3
	s_waitcnt vmcnt(11)
	v_lshlrev_b32_e32 v122, 16, v108
	v_and_b32_e32 v123, 0xffff0000, v108
	v_lshlrev_b32_e32 v124, 16, v109
	s_waitcnt vmcnt(10)
	v_lshlrev_b32_e32 v120, 16, v110
	v_and_b32_e32 v121, 0xffff0000, v110
	v_lshlrev_b32_e32 v126, 16, v111
	v_and_b32_e32 v127, 0xffff0000, v111
	v_and_b32_e32 v125, 0xffff0000, v109
	v_sub_f32_e32 v109, v100, v123
	v_sub_f32_e32 v108, v98, v122
	v_sub_f32_e32 v100, v99, v124
	v_sub_f32_e32 v99, v105, v127
	v_sub_f32_e32 v98, v104, v126
	v_sub_f32_e32 v103, v103, v121
	v_sub_f32_e32 v102, v102, v120
	v_sub_f32_e32 v101, v101, v125
	v_pk_fma_f32 v[102:103], v[48:49], v[102:103], v[120:121]
	v_pk_fma_f32 v[98:99], v[50:51], v[98:99], v[126:127]
	v_pk_fma_f32 v[110:111], v[46:47], v[100:101], v[124:125]
	v_pk_fma_f32 v[108:109], v[44:45], v[108:109], v[122:123]
	v_pk_mul_f32 v[118:119], v[38:39], v[98:99]
	v_pk_mul_f32 v[116:117], v[36:37], v[102:103]
	v_pk_mul_f32 v[100:101], v[130:131], v[98:99]
	v_pk_mul_f32 v[102:103], v[128:129], v[102:103]
	v_pk_mul_f32 v[98:99], v[118:119], v[118:119]
	v_pk_mul_f32 v[104:105], v[116:117], v[116:117]
	v_pk_mul_f32 v[128:129], v[108:109], v[102:103]
	v_pk_mul_f32 v[130:131], v[110:111], v[100:101]
	v_pk_mov_b32 v[132:133], v[104:105], v[98:99] op_sel:[1,0]
	v_mov_b32_e32 v105, v99
	v_pk_mul_f32 v[98:99], v[42:43], v[130:131]
	v_pk_mul_f32 v[128:129], v[40:41], v[128:129]
	v_pk_add_f32 v[104:105], v[132:133], v[104:105]
	v_add_f32_e32 v28, v128, v129
	v_add_f32_e32 v32, v98, v99
	v_add_f32_e32 v56, v104, v105
	v_add_f32_e32 v28, v28, v32
	s_nop 0
	v_add_f32_dpp v32, v56, v56 quad_perm:[1,0,3,2] row_mask:0xf bank_mask:0xf bound_ctrl:1
	v_add_f32_dpp v28, v28, v28 quad_perm:[1,0,3,2] row_mask:0xf bank_mask:0xf bound_ctrl:1
	s_nop 0
	v_add_f32_dpp v32, v32, v32 quad_perm:[2,3,0,1] row_mask:0xf bank_mask:0xf bound_ctrl:1
	v_add_f32_dpp v28, v28, v28 quad_perm:[2,3,0,1] row_mask:0xf bank_mask:0xf bound_ctrl:1
	s_nop 0
	v_add_f32_dpp v191, v32, v32 row_half_mirror row_mask:0xf bank_mask:0xf bound_ctrl:1
	v_add_f32_dpp v28, v28, v28 row_half_mirror row_mask:0xf bank_mask:0xf bound_ctrl:1
	s_nop 0
	v_mov_b32_dpp v190, v191 row_mirror row_mask:0xf bank_mask:0xf
	v_mov_b32_dpp v24, v28 row_mirror row_mask:0xf bank_mask:0xf
	s_and_saveexec_b64 s[2:3], s[24:25]
	s_cbranch_execz .LBB0_337
	v_ashrrev_i32_e32 v107, 31, v106
	v_lshlrev_b64 v[98:99], 6, v[106:107]
	v_lshl_add_u64 v[98:99], s[26:27], 0, v[98:99]
	v_add_f32_e32 v24, v28, v24
	global_store_dword v[98:99], v24, off
; __device__ __forceinline__ f32x4 bf4(v2u u) { return (f32x4){bflo(u.x), bfhi(u.x), bflo(u.y), bfhi(u.y)}; }
; __device__ __forceinline__ void rw_chunk_prep(const Args& a, int head, int tc0, const LAS bf16* TDr, const LAS bf16* DAr, LAS unsigned char* lw_, int lane) {
;     ...
;         for (int i = 0; i < 4; ++i) {
;             const int tt = tt0 + i;
;             const f32x4 zr = bf4(*(const v2u*)(ZA + (size_t)tt * 3072 + cbase)), zk = bf4(*(const v2u*)(ZA + (size_t)tt * 3072 + 1024 + cbase)), zv = bf4(*(const v2u*)(ZA + (size_t)tt * 3072 + 2048 + cbase));
;             const f32x4 r = zr + (pr - zr) * mur, k = zk + (pk - zk) * muk, v = zv + (pv - zv) * muv;
;             pr = zr; pk = zk; pv = zv;
;             f32x4 lwv, alr;
; #pragma unroll
;             for (int cb = 0; cb < 4; ++cb) { const float x = -(w0[cb] + accw[cb][i]); const float sp = fmaxf(x, 0.f) + __logf(1.f + __expf(-fabsf(x))); lwv[cb] = -__expf(-sp - 0.5f); alr[cb] = __builtin_amdgcn_rcpf(1.f + __expf(-(a0[cb] + acca[cb][i]))); }
;             const f32x4 kkr = k * kkw, kmod = k * (1.f + (alr - 1.f) * kaw);
;             float ssq = (kkr.x * kkr.x + kkr.y * kkr.y) + (kkr.z * kkr.z + kkr.w * kkr.w);
;             const f32x4 rkk = r * kmod * rkw; float rkp = (rkk.x + rkk.y) + (rkk.z + rkk.w);
;             ssq = row16_sum(ssq); rkp = row16_sum(rkp);
;             const float inv = __builtin_amdgcn_rsqf(fmaxf(ssq, 1e-24f));
;             const f32x4 kk = kkr * inv;
;             rr[i] = r; km[i] = kmod; av[i] = -kk; bv[i] = kk * alr; lw[i] = lwv; vv[i] = v;
;             if (j == 0) RK[(size_t)tt * 16 + head] = rkp;
.LBB0_337:
	s_or_b64 exec, exec, s[2:3]
	v_or_b32_e32 v32, 1, v106
	v_mov_b64_e32 v[98:99], s[72:73]
	v_mad_i64_i32 v[98:99], s[2:3], v32, s44, v[98:99]
	v_lshl_add_u64 v[98:99], v[98:99], 0, v[66:67]
	s_waitcnt vmcnt(6)
	v_mov_b32_e32 v128, v206
	v_mov_b32_e32 v129, v207
	v_add_f32_e32 v24, v25, v60
	v_mul_f32_e32 v24, 0xbfb8aa3b, v24
	v_exp_f32_e32 v24, v24
	v_mov_b32_e32 v193, v67
	v_add_f32_e32 v24, 1.0, v24
	s_nop 0
	v_lshlrev_b32_e32 v104, 16, v128
	v_and_b32_e32 v105, 0xffff0000, v128
	v_lshlrev_b32_e32 v132, 16, v129
	v_and_b32_e32 v133, 0xffff0000, v129
	v_mov_b32_e32 v128, v208
	v_mov_b32_e32 v129, v209
	v_add_co_u32_e32 v98, vcc, s45, v98
	s_nop 0
	v_lshlrev_b32_e32 v134, 16, v128
	v_addc_co_u32_e32 v99, vcc, 0, v99, vcc
	v_mov_b32_e32 v98, v210
	v_mov_b32_e32 v99, v211
	v_and_b32_e32 v135, 0xffff0000, v128
	v_sub_f32_e32 v128, v122, v104
	v_sub_f32_e32 v122, v124, v132
	v_rcp_f32_e32 v124, v24
	v_add_f32_e32 v24, v29, v61
	v_mul_f32_e32 v24, 0xbfb8aa3b, v24
	v_exp_f32_e32 v24, v24
	v_lshlrev_b32_e32 v136, 16, v129
	v_and_b32_e32 v137, 0xffff0000, v129
	v_sub_f32_e32 v129, v123, v105
	v_add_f32_e32 v24, 1.0, v24
	v_sub_f32_e32 v123, v125, v133
	v_rcp_f32_e32 v125, v24
	v_add_f32_e32 v24, v33, v62
	v_mul_f32_e32 v24, 0xbfb8aa3b, v24
	v_exp_f32_e32 v24, v24
	v_sub_f32_e32 v130, v126, v136
	v_sub_f32_e32 v131, v127, v137
	v_sub_f32_e32 v139, v121, v135
	v_add_f32_e32 v24, 1.0, v24
	v_rcp_f32_e32 v126, v24
	v_add_f32_e32 v24, v57, v63
	v_mul_f32_e32 v24, 0xbfb8aa3b, v24
	v_exp_f32_e32 v24, v24
	v_sub_f32_e32 v138, v120, v134
	v_pk_fma_f32 v[28:29], v[48:49], v[138:139], v[134:135]
	v_pk_add_f32 v[138:139], v[124:125], -1.0 op_sel_hi:[1,0]
	v_add_f32_e32 v24, 1.0, v24
	v_rcp_f32_e32 v127, v24
	v_pk_fma_f32 v[24:25], v[50:51], v[130:131], v[136:137]
	v_pk_fma_f32 v[120:121], v[44:45], v[128:129], v[104:105]
	v_pk_mul_f32 v[128:129], v[38:39], v[24:25]
	v_pk_add_f32 v[56:57], v[126:127], -1.0 op_sel_hi:[1,0]
	v_pk_mul_f32 v[130:131], v[36:37], v[28:29]
	v_pk_fma_f32 v[138:139], v[52:53], v[138:139], 1.0 op_sel_hi:[1,1,0]
	v_pk_fma_f32 v[56:57], v[54:55], v[56:57], 1.0 op_sel_hi:[1,1,0]
	v_pk_mul_f32 v[28:29], v[138:139], v[28:29]
	v_pk_mul_f32 v[24:25], v[56:57], v[24:25]
	v_pk_mul_f32 v[56:57], v[128:129], v[128:129]
	v_pk_mul_f32 v[138:139], v[130:131], v[130:131]
	v_pk_fma_f32 v[122:123], v[46:47], v[122:123], v[132:133]
	v_pk_mov_b32 v[140:141], v[138:139], v[56:57] op_sel:[1,0]
	v_mov_b32_e32 v139, v57
	v_pk_add_f32 v[56:57], v[140:141], v[138:139]
	v_pk_mul_f32 v[138:139], v[122:123], v[24:25]
	v_add_f32_e32 v33, v56, v57
	v_pk_mul_f32 v[56:57], v[120:121], v[28:29]
	v_pk_mul_f32 v[138:139], v[42:43], v[138:139]
	v_pk_mul_f32 v[56:57], v[40:41], v[56:57]
	v_add_f32_dpp v33, v33, v33 quad_perm:[1,0,3,2] row_mask:0xf bank_mask:0xf bound_ctrl:1
	v_add_f32_e32 v56, v56, v57
	v_add_f32_e32 v57, v138, v139
	v_add_f32_e32 v56, v56, v57
	v_add_f32_dpp v33, v33, v33 quad_perm:[2,3,0,1] row_mask:0xf bank_mask:0xf bound_ctrl:1
	v_mov_b32_e32 v57, v67
	s_nop 0
	v_add_f32_dpp v192, v33, v33 row_half_mirror row_mask:0xf bank_mask:0xf bound_ctrl:1
	v_add_f32_dpp v33, v56, v56 quad_perm:[1,0,3,2] row_mask:0xf bank_mask:0xf bound_ctrl:1
	s_nop 0
	v_mov_b32_dpp v193, v192 row_mirror row_mask:0xf bank_mask:0xf
	v_add_f32_dpp v33, v33, v33 quad_perm:[2,3,0,1] row_mask:0xf bank_mask:0xf bound_ctrl:1
	s_nop 1
	v_add_f32_dpp v56, v33, v33 row_half_mirror row_mask:0xf bank_mask:0xf bound_ctrl:1
	s_nop 1
	v_mov_b32_dpp v57, v56 row_mirror row_mask:0xf bank_mask:0xf
	s_and_saveexec_b64 s[2:3], s[24:25]
	s_cbranch_execz .LBB0_339
	v_ashrrev_i32_e32 v33, 31, v32
	v_lshlrev_b64 v[32:33], 6, v[32:33]
	v_lshl_add_u64 v[32:33], s[26:27], 0, v[32:33]
	v_add_f32_e32 v56, v56, v57
	global_store_dword v[32:33], v56, off
; __device__ __forceinline__ f32x4 bf4(v2u u) { return (f32x4){bflo(u.x), bfhi(u.x), bflo(u.y), bfhi(u.y)}; }
; __device__ __forceinline__ void rw_chunk_prep(const Args& a, int head, int tc0, const LAS bf16* TDr, const LAS bf16* DAr, LAS unsigned char* lw_, int lane) {
;     ...
;         for (int i = 0; i < 4; ++i) {
;             const int tt = tt0 + i;
;             const f32x4 zr = bf4(*(const v2u*)(ZA + (size_t)tt * 3072 + cbase)), zk = bf4(*(const v2u*)(ZA + (size_t)tt * 3072 + 1024 + cbase)), zv = bf4(*(const v2u*)(ZA + (size_t)tt * 3072 + 2048 + cbase));
;             const f32x4 r = zr + (pr - zr) * mur, k = zk + (pk - zk) * muk, v = zv + (pv - zv) * muv;
;             pr = zr; pk = zk; pv = zv;
;             f32x4 lwv, alr;
; #pragma unroll
;             for (int cb = 0; cb < 4; ++cb) { const float x = -(w0[cb] + accw[cb][i]); const float sp = fmaxf(x, 0.f) + __logf(1.f + __expf(-fabsf(x))); lwv[cb] = -__expf(-sp - 0.5f); alr[cb] = __builtin_amdgcn_rcpf(1.f + __expf(-(a0[cb] + acca[cb][i]))); }
;             const f32x4 kkr = k * kkw, kmod = k * (1.f + (alr - 1.f) * kaw);
;             float ssq = (kkr.x * kkr.x + kkr.y * kkr.y) + (kkr.z * kkr.z + kkr.w * kkr.w);
;             const f32x4 rkk = r * kmod * rkw; float rkp = (rkk.x + rkk.y) + (rkk.z + rkk.w);
;             ssq = row16_sum(ssq); rkp = row16_sum(rkp);
;             const float inv = __builtin_amdgcn_rsqf(fmaxf(ssq, 1e-24f));
;             const f32x4 kk = kkr * inv;
;             rr[i] = r; km[i] = kmod; av[i] = -kk; bv[i] = kk * alr; lw[i] = lwv; vv[i] = v;
;             if (j == 0) RK[(size_t)tt * 16 + head] = rkp;
.LBB0_339:
	s_or_b64 exec, exec, s[2:3]
	v_or_b32_e32 v152, 2, v106
	v_mov_b64_e32 v[32:33], s[72:73]
	v_mad_i64_i32 v[32:33], s[2:3], v152, s44, v[32:33]
	v_lshl_add_u64 v[32:33], v[32:33], 0, v[66:67]
	s_waitcnt vmcnt(3)
	v_mov_b32_e32 v56, v212
	v_mov_b32_e32 v57, v213
	v_add_f32_e32 v26, v26, v60
	v_mul_f32_e32 v26, 0xbfb8aa3b, v26
	v_exp_f32_e32 v26, v26
	s_nop 0
	v_lshlrev_b32_e32 v144, 16, v56
	v_and_b32_e32 v145, 0xffff0000, v56
	v_lshlrev_b32_e32 v146, 16, v57
	v_and_b32_e32 v147, 0xffff0000, v57
	v_mov_b32_e32 v56, v214
	v_mov_b32_e32 v57, v215
	v_add_co_u32_e32 v32, vcc, s45, v32
	v_add_f32_e32 v26, 1.0, v26
	s_nop 0
	v_addc_co_u32_e32 v33, vcc, 0, v33, vcc
	v_mov_b32_e32 v32, v216
	v_mov_b32_e32 v33, v217
	s_nop 0
	v_lshlrev_b32_e32 v150, 16, v57
	v_sub_f32_e32 v140, v136, v150
	v_rcp_f32_e32 v136, v26
	v_add_f32_e32 v26, v30, v61
	v_mul_f32_e32 v26, 0xbfb8aa3b, v26
	v_exp_f32_e32 v26, v26
	v_and_b32_e32 v151, 0xffff0000, v57
	v_sub_f32_e32 v141, v137, v151
	v_lshlrev_b32_e32 v148, 16, v56
	v_add_f32_e32 v26, 1.0, v26
	v_rcp_f32_e32 v137, v26
	v_add_f32_e32 v26, v34, v62
	v_mul_f32_e32 v26, 0xbfb8aa3b, v26
	v_exp_f32_e32 v26, v26
	v_and_b32_e32 v149, 0xffff0000, v56
	v_sub_f32_e32 v57, v105, v145
	v_sub_f32_e32 v56, v104, v144
	v_add_f32_e32 v26, 1.0, v26
	v_rcp_f32_e32 v138, v26
	v_add_f32_e32 v26, v58, v63
	v_mul_f32_e32 v26, 0xbfb8aa3b, v26
	v_exp_f32_e32 v26, v26
	v_sub_f32_e32 v105, v133, v147
	v_sub_f32_e32 v104, v132, v146
	v_sub_f32_e32 v143, v135, v149
	v_add_f32_e32 v26, 1.0, v26
	v_rcp_f32_e32 v139, v26
	v_sub_f32_e32 v142, v134, v148
	v_pk_fma_f32 v[134:135], v[46:47], v[104:105], v[146:147]
	v_pk_fma_f32 v[132:133], v[44:45], v[56:57], v[144:145]
	v_pk_fma_f32 v[104:105], v[48:49], v[142:143], v[148:149]
	v_pk_fma_f32 v[56:57], v[50:51], v[140:141], v[150:151]
	v_pk_add_f32 v[194:195], v[138:139], -1.0 op_sel_hi:[1,0]
	v_pk_add_f32 v[196:197], v[136:137], -1.0 op_sel_hi:[1,0]
	v_pk_mul_f32 v[140:141], v[38:39], v[56:57]
	v_pk_mul_f32 v[142:143], v[36:37], v[104:105]
	v_pk_fma_f32 v[196:197], v[52:53], v[196:197], 1.0 op_sel_hi:[1,1,0]
	v_pk_fma_f32 v[194:195], v[54:55], v[194:195], 1.0 op_sel_hi:[1,1,0]
	v_pk_mul_f32 v[104:105], v[196:197], v[104:105]
	v_pk_mul_f32 v[56:57], v[194:195], v[56:57]
	v_pk_mul_f32 v[194:195], v[140:141], v[140:141]
	v_pk_mul_f32 v[196:197], v[142:143], v[142:143]
	s_nop 0
	v_pk_mov_b32 v[198:199], v[196:197], v[194:195] op_sel:[1,0]
	v_mov_b32_e32 v197, v195
	v_pk_add_f32 v[194:195], v[198:199], v[196:197]
	v_pk_mul_f32 v[196:197], v[134:135], v[56:57]
	v_add_f32_e32 v26, v194, v195
	v_pk_mul_f32 v[194:195], v[132:133], v[104:105]
	v_pk_mul_f32 v[196:197], v[42:43], v[196:197]
	v_pk_mul_f32 v[194:195], v[40:41], v[194:195]
	v_add_f32_e32 v34, v196, v197
	v_add_f32_e32 v30, v194, v195
	v_add_f32_dpp v26, v26, v26 quad_perm:[1,0,3,2] row_mask:0xf bank_mask:0xf bound_ctrl:1
	v_add_f32_e32 v30, v30, v34
	v_mov_b32_e32 v195, v67
	v_add_f32_dpp v26, v26, v26 quad_perm:[2,3,0,1] row_mask:0xf bank_mask:0xf bound_ctrl:1
	s_nop 1
	v_add_f32_dpp v194, v26, v26 row_half_mirror row_mask:0xf bank_mask:0xf bound_ctrl:1
	v_add_f32_dpp v26, v30, v30 quad_perm:[1,0,3,2] row_mask:0xf bank_mask:0xf bound_ctrl:1
	v_mov_b32_e32 v30, v67
	v_mov_b32_dpp v195, v194 row_mirror row_mask:0xf bank_mask:0xf
	v_add_f32_dpp v26, v26, v26 quad_perm:[2,3,0,1] row_mask:0xf bank_mask:0xf bound_ctrl:1
	s_nop 1
	v_add_f32_dpp v26, v26, v26 row_half_mirror row_mask:0xf bank_mask:0xf bound_ctrl:1
	s_nop 1
	v_mov_b32_dpp v30, v26 row_mirror row_mask:0xf bank_mask:0xf
	s_and_saveexec_b64 s[2:3], s[24:25]
	s_cbranch_execz .LBB0_341
	v_ashrrev_i32_e32 v153, 31, v152
	v_lshlrev_b64 v[152:153], 6, v[152:153]
	v_lshl_add_u64 v[152:153], s[26:27], 0, v[152:153]
	v_add_f32_e32 v26, v26, v30
	global_store_dword v[152:153], v26, off
.LBB0_341:
	s_or_b64 exec, exec, s[2:3]
	v_or_b32_e32 v152, 3, v106
	v_mov_b64_e32 v[106:107], s[72:73]
	v_mad_i64_i32 v[106:107], s[2:3], v152, s44, v[106:107]
	v_lshl_add_u64 v[106:107], v[106:107], 0, v[66:67]
	s_cmp_eq_u64 s[24:25], 0
	s_cbranch_scc1 .Lrw_t3_w0
	s_waitcnt vmcnt(3)
	s_branch .Lrw_t3_go

; __device__ __forceinline__ f32x4 bf4(v2u u) { return (f32x4){bflo(u.x), bfhi(u.x), bflo(u.y), bfhi(u.y)}; }
; __device__ __forceinline__ void rw_chunk_prep(const Args& a, int head, int tc0, const LAS bf16* TDr, const LAS bf16* DAr, LAS unsigned char* lw_, int lane) {
;     ...
;         for (int i = 0; i < 4; ++i) {
;             const int tt = tt0 + i;
;             const f32x4 zr = bf4(*(const v2u*)(ZA + (size_t)tt * 3072 + cbase)), zk = bf4(*(const v2u*)(ZA + (size_t)tt * 3072 + 1024 + cbase)), zv = bf4(*(const v2u*)(ZA + (size_t)tt * 3072 + 2048 + cbase));
;             const f32x4 r = zr + (pr - zr) * mur, k = zk + (pk - zk) * muk, v = zv + (pv - zv) * muv;
;             pr = zr; pk = zk; pv = zv;
;             f32x4 lwv, alr;
; #pragma unroll
;             for (int cb = 0; cb < 4; ++cb) { const float x = -(w0[cb] + accw[cb][i]); const float sp = fmaxf(x, 0.f) + __logf(1.f + __expf(-fabsf(x))); lwv[cb] = -__expf(-sp - 0.5f); alr[cb] = __builtin_amdgcn_rcpf(1.f + __expf(-(a0[cb] + acca[cb][i]))); }
;             const f32x4 kkr = k * kkw, kmod = k * (1.f + (alr - 1.f) * kaw);
;             float ssq = (kkr.x * kkr.x + kkr.y * kkr.y) + (kkr.z * kkr.z + kkr.w * kkr.w);
;             const f32x4 rkk = r * kmod * rkw; float rkp = (rkk.x + rkk.y) + (rkk.z + rkk.w);
;             ssq = row16_sum(ssq); rkp = row16_sum(rkp);
;             const float inv = __builtin_amdgcn_rsqf(fmaxf(ssq, 1e-24f));
;             const f32x4 kk = kkr * inv;
;             rr[i] = r; km[i] = kmod; av[i] = -kk; bv[i] = kk * alr; lw[i] = lwv; vv[i] = v;
;             if (j == 0) RK[(size_t)tt * 16 + head] = rkp;
.Lrw_t3_go:
	v_mov_b32_e32 v198, v218
	v_mov_b32_e32 v199, v219
	v_mov_b32_e32 v200, v220
	v_mov_b32_e32 v201, v221
	v_add_co_u32_e32 v106, vcc, s45, v106
	v_add_f32_e32 v26, v27, v60
	s_nop 0
	v_addc_co_u32_e32 v107, vcc, 0, v107, vcc
	v_mov_b32_e32 v106, v222
	v_mov_b32_e32 v107, v223
	v_add_f32_e32 v27, v31, v61
	v_add_f32_e32 v30, v35, v62
	v_add_f32_e32 v31, v59, v63
	v_mul_f32_e32 v26, 0xbfb8aa3b, v26
	v_mul_f32_e32 v27, 0xbfb8aa3b, v27
	v_mul_f32_e32 v30, 0xbfb8aa3b, v30
	v_mul_f32_e32 v31, 0xbfb8aa3b, v31
	v_exp_f32_e32 v26, v26
	v_exp_f32_e32 v27, v27
	v_exp_f32_e32 v30, v30
	v_exp_f32_e32 v31, v31
	v_add_f32_e32 v26, 1.0, v26
	v_add_f32_e32 v27, 1.0, v27
	v_add_f32_e32 v30, 1.0, v30
	v_add_f32_e32 v31, 1.0, v31
	v_rcp_f32_e32 v58, v26
	v_rcp_f32_e32 v34, v30
	v_rcp_f32_e32 v35, v31
	v_rcp_f32_e32 v59, v27
	v_mov_b32_e32 v196, v67
	v_mov_b32_e32 v62, v67
	v_pk_add_f32 v[26:27], v[34:35], -1.0 op_sel_hi:[1,0]
	v_pk_add_f32 v[30:31], v[58:59], -1.0 op_sel_hi:[1,0]
	v_pk_fma_f32 v[26:27], v[54:55], v[26:27], 1.0 op_sel_hi:[1,1,0]
	v_pk_fma_f32 v[30:31], v[52:53], v[30:31], 1.0 op_sel_hi:[1,1,0]
	v_mov_b32_e32 v66, 0
	s_nop 0
	v_lshlrev_b32_e32 v52, 16, v198
	v_and_b32_e32 v53, 0xffff0000, v198
	v_lshlrev_b32_e32 v54, 16, v199
	v_and_b32_e32 v55, 0xffff0000, v199
	s_nop 0
	v_lshlrev_b32_e32 v198, 16, v200
	v_and_b32_e32 v199, 0xffff0000, v200
	v_lshlrev_b32_e32 v200, 16, v201
	v_and_b32_e32 v201, 0xffff0000, v201
	v_sub_f32_e32 v145, v145, v53
	v_sub_f32_e32 v144, v144, v52
	v_sub_f32_e32 v61, v147, v55
	v_sub_f32_e32 v60, v146, v54
	v_sub_f32_e32 v147, v151, v201
	v_sub_f32_e32 v146, v150, v200
	v_sub_f32_e32 v149, v149, v199
	v_sub_f32_e32 v148, v148, v198
	v_pk_fma_f32 v[60:61], v[46:47], v[60:61], v[54:55]
	v_pk_fma_f32 v[144:145], v[44:45], v[144:145], v[52:53]
	v_pk_fma_f32 v[44:45], v[48:49], v[148:149], v[198:199]
	v_pk_fma_f32 v[46:47], v[50:51], v[146:147], v[200:201]
	v_pk_mul_f32 v[36:37], v[36:37], v[44:45]
	v_pk_mul_f32 v[38:39], v[38:39], v[46:47]
	v_pk_mul_f32 v[26:27], v[26:27], v[46:47]
	v_pk_mul_f32 v[30:31], v[30:31], v[44:45]
	v_pk_mul_f32 v[44:45], v[38:39], v[38:39]
	v_pk_mul_f32 v[46:47], v[36:37], v[36:37]
	v_pk_mul_f32 v[48:49], v[144:145], v[30:31]
	v_pk_mul_f32 v[50:51], v[60:61], v[26:27]
	v_pk_mov_b32 v[52:53], v[46:47], v[44:45] op_sel:[1,0]
	v_mov_b32_e32 v47, v45
	v_pk_mul_f32 v[42:43], v[42:43], v[50:51]
	v_pk_mul_f32 v[40:41], v[40:41], v[48:49]
	v_pk_add_f32 v[44:45], v[52:53], v[46:47]
	v_add_f32_e32 v40, v40, v41
	v_add_f32_e32 v41, v42, v43
	v_add_f32_e32 v42, v44, v45
	v_add_f32_e32 v40, v40, v41
	s_nop 0
	v_add_f32_dpp v41, v42, v42 quad_perm:[1,0,3,2] row_mask:0xf bank_mask:0xf bound_ctrl:1
	v_add_f32_dpp v40, v40, v40 quad_perm:[1,0,3,2] row_mask:0xf bank_mask:0xf bound_ctrl:1
	s_nop 0
	v_add_f32_dpp v41, v41, v41 quad_perm:[2,3,0,1] row_mask:0xf bank_mask:0xf bound_ctrl:1
	v_add_f32_dpp v42, v40, v40 quad_perm:[2,3,0,1] row_mask:0xf bank_mask:0xf bound_ctrl:1
	s_nop 0
	v_add_f32_dpp v40, v41, v41 row_half_mirror row_mask:0xf bank_mask:0xf bound_ctrl:1
	v_add_f32_dpp v41, v42, v42 row_half_mirror row_mask:0xf bank_mask:0xf bound_ctrl:1
	s_nop 0
	v_mov_b32_dpp v196, v40 row_mirror row_mask:0xf bank_mask:0xf
	v_mov_b32_dpp v62, v41 row_mirror row_mask:0xf bank_mask:0xf
	s_and_saveexec_b64 s[2:3], s[24:25]
	s_cbranch_execz .LBB0_343
	v_ashrrev_i32_e32 v153, 31, v152
	v_lshlrev_b64 v[42:43], 6, v[152:153]
	v_lshl_add_u64 v[42:43], s[26:27], 0, v[42:43]
	v_add_f32_e32 v41, v41, v62
	v_mov_b32_e32 v66, 1.0
	global_store_dword v[42:43], v41, off
